# attention: split the 64 v_pk_add_f32 (C-operand init) into scalar v_sub_f32 pairs, bit-identical
# speedup vs baseline: 1.0141x; 1.0141x over previous
; #define WAIT_BAR(N) asm volatile("s_waitcnt vmcnt(" #N ") lgkmcnt(0)\n\ts_barrier":::"memory")
;   #define RESC() do{ if(resc){ asm volatile("s_waitcnt lgkmcnt(0)":::"memory"); \
;       _Pragma("unroll") for(int d_=0;d_<2;++d_) _Pragma("unroll") for(int r=0;r<16;++r)o[d_][r]*=wsf[crow(r,hi)]; } }while(0)
;   #define ROT() do{sl_prev=sl_cur;sl_cur=sl_next;sl_next=(sl_next==(NSLOT-1)*SLOTB)?0:sl_next+SLOTB;}while(0)
; template<int THRL> __device__ __forceinline__ void attn_unit(int b,int h,int qb,const bf16*Q,const bf16*__restrict__ K,const bf16*__restrict__ V,const unsigned short*GB,unsigned short*Y,const float*Fcum,int ts,char*shm){
;     ...
;   int t=1;
;     ...
;   for(;t+5<NT;t+=2){
;     STEP(pB0,pB1,pA0,pA1,t,true,true,true);     WAIT_BAR(2); RESC(); ROT();
;     STEP(pA0,pA1,pB0,pB1,t+1,true,true,true);   WAIT_BAR(2); RESC(); ROT();
.LBB0_218:
	s_waitcnt lgkmcnt(14)
	v_mfma_f32_32x32x16_bf16 v[16:31], v[126:129], v[166:169], v[16:31]
	v_exp_f32_e32 v32, v32
	v_exp_f32_e32 v33, v33
	v_exp_f32_e32 v34, v34
	v_exp_f32_e32 v35, v35
	ds_read_b128 v[64:67], v186
	s_waitcnt lgkmcnt(0)
	v_sub_f32_e32 v80, v208, v64
	v_sub_f32_e32 v81, v208, v65
	v_sub_f32_e32 v82, v208, v66
	v_sub_f32_e32 v83, v208, v67
	v_mfma_f32_32x32x16_bf16 v[0:15], v[126:129], v[162:165], v[0:15]
	v_exp_f32_e32 v36, v36
	v_exp_f32_e32 v37, v37
	v_exp_f32_e32 v38, v38
	v_exp_f32_e32 v39, v39
	ds_read_b128 v[64:67], v186 offset:32
	s_waitcnt lgkmcnt(0)
	v_sub_f32_e32 v84, v208, v64
	v_sub_f32_e32 v85, v208, v65
	v_sub_f32_e32 v86, v208, v66
	v_sub_f32_e32 v87, v208, v67
	v_add_u32_e32 v126, s31, v239
	ds_read_b128 v[170:173], v126
	ds_read_b128 v[162:165], v126 offset:512
	v_mfma_f32_32x32x16_bf16 v[16:31], v[122:125], v[158:161], v[16:31]
	v_exp_f32_e32 v40, v40
	v_exp_f32_e32 v41, v41
	v_exp_f32_e32 v42, v42
	v_exp_f32_e32 v43, v43
	ds_read_b128 v[64:67], v186 offset:64
	s_waitcnt lgkmcnt(0)
	v_sub_f32_e32 v88, v208, v64
	v_sub_f32_e32 v89, v208, v65
	v_sub_f32_e32 v90, v208, v66
	v_sub_f32_e32 v91, v208, v67
	ds_read_b128 v[166:169], v126 offset:2048
	ds_read_b128 v[158:161], v126 offset:2560
	v_mfma_f32_32x32x16_bf16 v[0:15], v[122:125], v[154:157], v[0:15]
	v_exp_f32_e32 v44, v44
	v_exp_f32_e32 v45, v45
	v_exp_f32_e32 v46, v46
	v_exp_f32_e32 v47, v47
	ds_read_b128 v[64:67], v186 offset:96
	s_waitcnt lgkmcnt(0)
	v_sub_f32_e32 v92, v208, v64
	v_sub_f32_e32 v93, v208, v65
	v_sub_f32_e32 v94, v208, v66
	v_sub_f32_e32 v95, v208, v67
	ds_read_b128 v[154:157], v126 offset:4096
	ds_read_b128 v[138:141], v126 offset:4608
	v_mfma_f32_32x32x16_bf16 v[16:31], v[118:121], v[150:153], v[16:31]
	v_exp_f32_e32 v48, v48
	v_exp_f32_e32 v49, v49
	v_exp_f32_e32 v50, v50
	v_exp_f32_e32 v51, v51
	ds_read_b128 v[64:67], v186 offset:128
	s_waitcnt lgkmcnt(0)
	v_sub_f32_e32 v64, v208, v64
	v_sub_f32_e32 v65, v208, v65
	v_sub_f32_e32 v66, v208, v66
	v_sub_f32_e32 v67, v208, v67
	ds_read_b128 v[150:153], v126 offset:6144
	ds_read_b128 v[130:133], v126 offset:6656
	v_mfma_f32_32x32x16_bf16 v[0:15], v[118:121], v[146:149], v[0:15]
	v_exp_f32_e32 v52, v52
	v_exp_f32_e32 v53, v53
	v_exp_f32_e32 v54, v54
	v_exp_f32_e32 v55, v55
	ds_read_b128 v[68:71], v186 offset:160
	s_waitcnt lgkmcnt(0)
	v_sub_f32_e32 v68, v208, v68
	v_sub_f32_e32 v69, v208, v69
	v_sub_f32_e32 v70, v208, v70
	v_sub_f32_e32 v71, v208, v71
	v_mfma_f32_32x32x16_bf16 v[16:31], v[114:117], v[142:145], v[16:31]
	v_exp_f32_e32 v56, v56
	v_exp_f32_e32 v57, v57
	v_exp_f32_e32 v58, v58
	v_exp_f32_e32 v59, v59
	ds_read_b128 v[72:75], v186 offset:192
	s_waitcnt lgkmcnt(0)
	v_sub_f32_e32 v72, v208, v72
	v_sub_f32_e32 v73, v208, v73
	v_sub_f32_e32 v74, v208, v74
	v_sub_f32_e32 v75, v208, v75
	v_mfma_f32_32x32x16_bf16 v[0:15], v[114:117], v[134:137], v[0:15]
	v_exp_f32_e32 v60, v60
	v_exp_f32_e32 v61, v61
	v_exp_f32_e32 v62, v62
	v_exp_f32_e32 v63, v63
	ds_read_b128 v[76:79], v186 offset:224
	s_waitcnt lgkmcnt(0)
	v_sub_f32_e32 v76, v208, v76
	v_sub_f32_e32 v77, v208, v77
	v_sub_f32_e32 v78, v208, v78
	v_sub_f32_e32 v79, v208, v79
	s_waitcnt vmcnt(2) lgkmcnt(0)
	s_barrier
	s_andn2_b64 vcc, exec, s[52:53]
	s_cbranch_vccnz .LBB0_220
	s_waitcnt lgkmcnt(0)
	ds_read_b128 v[134:137], v236 offset:49248
	ds_read_b128 v[142:145], v236 offset:49216
	ds_read_b128 v[146:149], v236 offset:49184
	ds_read_b128 v[174:177], v236 offset:49152
	s_waitcnt lgkmcnt(3)
	v_pk_mul_f32 v[30:31], v[30:31], v[136:137]
	s_waitcnt lgkmcnt(2)
	v_pk_mul_f32 v[26:27], v[26:27], v[144:145]
	s_waitcnt lgkmcnt(1)
	v_pk_mul_f32 v[22:23], v[22:23], v[148:149]
	s_waitcnt lgkmcnt(0)
	v_pk_mul_f32 v[18:19], v[18:19], v[176:177]
	v_pk_mul_f32 v[28:29], v[28:29], v[134:135]
	v_pk_mul_f32 v[24:25], v[24:25], v[142:143]
	v_pk_mul_f32 v[20:21], v[20:21], v[146:147]
	v_pk_mul_f32 v[16:17], v[16:17], v[174:175]
	v_pk_mul_f32 v[14:15], v[14:15], v[136:137]
	v_pk_mul_f32 v[10:11], v[10:11], v[144:145]
	v_pk_mul_f32 v[6:7], v[6:7], v[148:149]
	v_pk_mul_f32 v[2:3], v[2:3], v[176:177]
	v_pk_mul_f32 v[12:13], v[12:13], v[134:135]
	v_pk_mul_f32 v[8:9], v[8:9], v[142:143]
	v_pk_mul_f32 v[4:5], v[4:5], v[146:147]
	v_pk_mul_f32 v[0:1], v[0:1], v[174:175]

; #define WAIT_BAR(N) asm volatile("s_waitcnt vmcnt(" #N ") lgkmcnt(0)\n\ts_barrier":::"memory")
;   #define RESC() do{ if(resc){ asm volatile("s_waitcnt lgkmcnt(0)":::"memory"); \
;       _Pragma("unroll") for(int d_=0;d_<2;++d_) _Pragma("unroll") for(int r=0;r<16;++r)o[d_][r]*=wsf[crow(r,hi)]; } }while(0)
;   #define ROT() do{sl_prev=sl_cur;sl_cur=sl_next;sl_next=(sl_next==(NSLOT-1)*SLOTB)?0:sl_next+SLOTB;}while(0)
; template<int THRL> __device__ __forceinline__ void attn_unit(int b,int h,int qb,const bf16*Q,const bf16*__restrict__ K,const bf16*__restrict__ V,const unsigned short*GB,unsigned short*Y,const float*Fcum,int ts,char*shm){
;     ...
;   int t=1;
;     ...
;   for(;t+5<NT;t+=2){
;     STEP(pB0,pB1,pA0,pA1,t,true,true,true);     WAIT_BAR(2); RESC(); ROT();
;     STEP(pA0,pA1,pB0,pB1,t+1,true,true,true);   WAIT_BAR(2); RESC(); ROT();
.LBB0_221:
	s_waitcnt lgkmcnt(14)
	v_mfma_f32_32x32x16_bf16 v[16:31], v[126:129], v[178:181], v[16:31]
	v_exp_f32_e32 v80, v80
	v_exp_f32_e32 v81, v81
	v_exp_f32_e32 v82, v82
	v_exp_f32_e32 v83, v83
	ds_read_b128 v[32:35], v186 offset:256
	s_waitcnt lgkmcnt(0)
	v_sub_f32_e32 v32, v208, v32
	v_sub_f32_e32 v33, v208, v33
	v_sub_f32_e32 v34, v208, v34
	v_sub_f32_e32 v35, v208, v35
	v_mfma_f32_32x32x16_bf16 v[0:15], v[126:129], v[146:149], v[0:15]
	v_exp_f32_e32 v84, v84
	v_exp_f32_e32 v85, v85
	v_exp_f32_e32 v86, v86
	v_exp_f32_e32 v87, v87
	ds_read_b128 v[36:39], v186 offset:288
	s_waitcnt lgkmcnt(0)
	v_sub_f32_e32 v36, v208, v36
	v_sub_f32_e32 v37, v208, v37
	v_sub_f32_e32 v38, v208, v38
	v_sub_f32_e32 v39, v208, v39
	v_add_u32_e32 v126, s6, v239
	ds_read_b128 v[158:161], v126
	ds_read_b128 v[150:153], v126 offset:512
	v_mfma_f32_32x32x16_bf16 v[16:31], v[122:125], v[142:145], v[16:31]
	v_exp_f32_e32 v88, v88
	v_exp_f32_e32 v89, v89
	v_exp_f32_e32 v90, v90
	v_exp_f32_e32 v91, v91
	ds_read_b128 v[40:43], v186 offset:320
	s_waitcnt lgkmcnt(0)
	v_sub_f32_e32 v40, v208, v40
	v_sub_f32_e32 v41, v208, v41
	v_sub_f32_e32 v42, v208, v42
	v_sub_f32_e32 v43, v208, v43
	ds_read_b128 v[154:157], v126 offset:2048
	ds_read_b128 v[142:145], v126 offset:2560
	v_mfma_f32_32x32x16_bf16 v[0:15], v[122:125], v[134:137], v[0:15]
	v_exp_f32_e32 v92, v92
	v_exp_f32_e32 v93, v93
	v_exp_f32_e32 v94, v94
	v_exp_f32_e32 v95, v95
	ds_read_b128 v[44:47], v186 offset:352
	s_waitcnt lgkmcnt(0)
	v_sub_f32_e32 v44, v208, v44
	v_sub_f32_e32 v45, v208, v45
	v_sub_f32_e32 v46, v208, v46
	v_sub_f32_e32 v47, v208, v47
	ds_read_b128 v[146:149], v126 offset:4096
	ds_read_b128 v[134:137], v126 offset:4608
	v_mfma_f32_32x32x16_bf16 v[16:31], v[118:121], v[174:177], v[16:31]
	v_exp_f32_e32 v64, v64
	v_exp_f32_e32 v65, v65
	v_exp_f32_e32 v66, v66
	v_exp_f32_e32 v67, v67
	ds_read_b128 v[48:51], v186 offset:384
	s_waitcnt lgkmcnt(0)
	v_sub_f32_e32 v48, v208, v48
	v_sub_f32_e32 v49, v208, v49
	v_sub_f32_e32 v50, v208, v50
	v_sub_f32_e32 v51, v208, v51
	ds_read_b128 v[138:141], v126 offset:6144
	ds_read_b128 v[130:133], v126 offset:6656
	v_mfma_f32_32x32x16_bf16 v[0:15], v[118:121], v[170:173], v[0:15]
	v_exp_f32_e32 v68, v68
	v_exp_f32_e32 v69, v69
	v_exp_f32_e32 v70, v70
	v_exp_f32_e32 v71, v71
	ds_read_b128 v[52:55], v186 offset:416
	s_waitcnt lgkmcnt(0)
	v_sub_f32_e32 v52, v208, v52
	v_sub_f32_e32 v53, v208, v53
	v_sub_f32_e32 v54, v208, v54
	v_sub_f32_e32 v55, v208, v55
	v_mfma_f32_32x32x16_bf16 v[16:31], v[114:117], v[166:169], v[16:31]
	v_exp_f32_e32 v72, v72
	v_exp_f32_e32 v73, v73
	v_exp_f32_e32 v74, v74
	v_exp_f32_e32 v75, v75
	ds_read_b128 v[56:59], v186 offset:448
	s_waitcnt lgkmcnt(0)
	v_sub_f32_e32 v56, v208, v56
	v_sub_f32_e32 v57, v208, v57
	v_sub_f32_e32 v58, v208, v58
	v_sub_f32_e32 v59, v208, v59
	v_mfma_f32_32x32x16_bf16 v[0:15], v[114:117], v[162:165], v[0:15]
	v_exp_f32_e32 v76, v76
	v_exp_f32_e32 v77, v77
	v_exp_f32_e32 v78, v78
	v_exp_f32_e32 v79, v79
	ds_read_b128 v[60:63], v186 offset:480
	s_waitcnt lgkmcnt(0)
	v_sub_f32_e32 v60, v208, v60
	v_sub_f32_e32 v61, v208, v61
	v_sub_f32_e32 v62, v208, v62
	v_sub_f32_e32 v63, v208, v63
	s_waitcnt vmcnt(2) lgkmcnt(0)
	s_barrier
	s_andn2_b64 vcc, exec, s[52:53]
	s_cbranch_vccnz .LBB0_223
	s_waitcnt lgkmcnt(0)
	ds_read_b128 v[162:165], v236 offset:49248
	ds_read_b128 v[166:169], v236 offset:49216
	ds_read_b128 v[170:173], v236 offset:49184
	ds_read_b128 v[174:177], v236 offset:49152
	s_waitcnt lgkmcnt(3)
	v_pk_mul_f32 v[30:31], v[30:31], v[164:165]
	s_waitcnt lgkmcnt(2)
	v_pk_mul_f32 v[26:27], v[26:27], v[168:169]
	s_waitcnt lgkmcnt(1)
	v_pk_mul_f32 v[22:23], v[22:23], v[172:173]
	s_waitcnt lgkmcnt(0)
	v_pk_mul_f32 v[18:19], v[18:19], v[176:177]
	v_pk_mul_f32 v[28:29], v[28:29], v[162:163]
	v_pk_mul_f32 v[24:25], v[24:25], v[166:167]
	v_pk_mul_f32 v[20:21], v[20:21], v[170:171]
	v_pk_mul_f32 v[16:17], v[16:17], v[174:175]
	v_pk_mul_f32 v[14:15], v[14:15], v[164:165]
	v_pk_mul_f32 v[10:11], v[10:11], v[168:169]
	v_pk_mul_f32 v[6:7], v[6:7], v[172:173]
	v_pk_mul_f32 v[2:3], v[2:3], v[176:177]
	v_pk_mul_f32 v[12:13], v[12:13], v[162:163]
	v_pk_mul_f32 v[8:9], v[8:9], v[166:167]
	v_pk_mul_f32 v[4:5], v[4:5], v[170:171]
	v_pk_mul_f32 v[0:1], v[0:1], v[174:175]

; #define WAIT_BAR(N) asm volatile("s_waitcnt vmcnt(" #N ") lgkmcnt(0)\n\ts_barrier":::"memory")
;   #define RESC() do{ if(resc){ asm volatile("s_waitcnt lgkmcnt(0)":::"memory"); \
;       _Pragma("unroll") for(int d_=0;d_<2;++d_) _Pragma("unroll") for(int r=0;r<16;++r)o[d_][r]*=wsf[crow(r,hi)]; } }while(0)
;   #define ROT() do{sl_prev=sl_cur;sl_cur=sl_next;sl_next=(sl_next==(NSLOT-1)*SLOTB)?0:sl_next+SLOTB;}while(0)
;   #define ENDW(tt) do{ if((tt)+3<NT){WAIT_BAR(2);} else if((tt)+2<NT){WAIT_BAR(1);} else {WAIT_BAR(0);} }while(0)
; template<int THRL> __device__ __forceinline__ void attn_unit(int b,int h,int qb,const bf16*Q,const bf16*__restrict__ K,const bf16*__restrict__ V,const unsigned short*GB,unsigned short*Y,const float*Fcum,int ts,char*shm){
;     ...
;   int t=1;
;     ...
;   for(;t+5<NT;t+=2){
;     STEP(pB0,pB1,pA0,pA1,t,true,true,true);     WAIT_BAR(2); RESC(); ROT();
;     STEP(pA0,pA1,pB0,pB1,t+1,true,true,true);   WAIT_BAR(2); RESC(); ROT();
;   }
;     ...
;   for(;t+1<NT;t+=2){
;     STEP(pB0,pB1,pA0,pA1,t,(t+3<NT),(t+1<NT),(t+1<NT));       ENDW(t);   RESC(); ROT();
.LBB0_245:
	s_waitcnt lgkmcnt(14)
	v_mfma_f32_32x32x16_bf16 v[16:31], v[126:129], v[186:189], v[16:31]
	v_exp_f32_e32 v32, v32
	v_exp_f32_e32 v33, v33
	v_exp_f32_e32 v34, v34
	v_exp_f32_e32 v35, v35
	ds_read_b128 v[64:67], v242
	s_waitcnt lgkmcnt(0)
	v_sub_f32_e32 v80, v208, v64
	v_sub_f32_e32 v81, v208, v65
	v_sub_f32_e32 v82, v208, v66
	v_sub_f32_e32 v83, v208, v67
	v_mfma_f32_32x32x16_bf16 v[0:15], v[126:129], v[158:161], v[0:15]
	v_exp_f32_e32 v36, v36
	v_exp_f32_e32 v37, v37
	v_exp_f32_e32 v38, v38
	v_exp_f32_e32 v39, v39
	ds_read_b128 v[64:67], v242 offset:32
	s_waitcnt lgkmcnt(0)
	v_sub_f32_e32 v84, v208, v64
	v_sub_f32_e32 v85, v208, v65
	v_sub_f32_e32 v86, v208, v66
	v_sub_f32_e32 v87, v208, v67
	v_add_u32_e32 v126, s21, v239
	ds_read_b128 v[158:161], v126
	ds_read_b128 v[150:153], v126 offset:512
	v_mfma_f32_32x32x16_bf16 v[16:31], v[122:125], v[182:185], v[16:31]
	v_exp_f32_e32 v40, v40
	v_exp_f32_e32 v41, v41
	v_exp_f32_e32 v42, v42
	v_exp_f32_e32 v43, v43
	ds_read_b128 v[64:67], v242 offset:64
	s_waitcnt lgkmcnt(0)
	v_sub_f32_e32 v88, v208, v64
	v_sub_f32_e32 v89, v208, v65
	v_sub_f32_e32 v90, v208, v66
	v_sub_f32_e32 v91, v208, v67
	ds_read_b128 v[154:157], v126 offset:2048
	ds_read_b128 v[142:145], v126 offset:2560
	v_mfma_f32_32x32x16_bf16 v[0:15], v[122:125], v[178:181], v[0:15]
	v_exp_f32_e32 v44, v44
	v_exp_f32_e32 v45, v45
	v_exp_f32_e32 v46, v46
	v_exp_f32_e32 v47, v47
	ds_read_b128 v[64:67], v242 offset:96
	s_waitcnt lgkmcnt(0)
	v_sub_f32_e32 v92, v208, v64
	v_sub_f32_e32 v93, v208, v65
	v_sub_f32_e32 v94, v208, v66
	v_sub_f32_e32 v95, v208, v67
	ds_read_b128 v[146:149], v126 offset:4096
	ds_read_b128 v[134:137], v126 offset:4608
	v_mfma_f32_32x32x16_bf16 v[16:31], v[118:121], v[174:177], v[16:31]
	v_exp_f32_e32 v48, v48
	v_exp_f32_e32 v49, v49
	v_exp_f32_e32 v50, v50
	v_exp_f32_e32 v51, v51
	ds_read_b128 v[64:67], v242 offset:128
	s_waitcnt lgkmcnt(0)
	v_sub_f32_e32 v64, v208, v64
	v_sub_f32_e32 v65, v208, v65
	v_sub_f32_e32 v66, v208, v66
	v_sub_f32_e32 v67, v208, v67
	ds_read_b128 v[138:141], v126 offset:6144
	ds_read_b128 v[130:133], v126 offset:6656
	v_mfma_f32_32x32x16_bf16 v[0:15], v[118:121], v[170:173], v[0:15]
	v_exp_f32_e32 v52, v52
	v_exp_f32_e32 v53, v53
	v_exp_f32_e32 v54, v54
	v_exp_f32_e32 v55, v55
	ds_read_b128 v[68:71], v242 offset:160
	s_waitcnt lgkmcnt(0)
	v_sub_f32_e32 v68, v208, v68
	v_sub_f32_e32 v69, v208, v69
	v_sub_f32_e32 v70, v208, v70
	v_sub_f32_e32 v71, v208, v71
	v_mfma_f32_32x32x16_bf16 v[16:31], v[114:117], v[166:169], v[16:31]
	v_exp_f32_e32 v56, v56
	v_exp_f32_e32 v57, v57
	v_exp_f32_e32 v58, v58
	v_exp_f32_e32 v59, v59
	ds_read_b128 v[72:75], v242 offset:192
	s_waitcnt lgkmcnt(0)
	v_sub_f32_e32 v72, v208, v72
	v_sub_f32_e32 v73, v208, v73
	v_sub_f32_e32 v74, v208, v74
	v_sub_f32_e32 v75, v208, v75
	v_mfma_f32_32x32x16_bf16 v[0:15], v[114:117], v[162:165], v[0:15]
	v_exp_f32_e32 v60, v60
	v_exp_f32_e32 v61, v61
	v_exp_f32_e32 v62, v62
	v_exp_f32_e32 v63, v63
	ds_read_b128 v[76:79], v242 offset:224
	s_waitcnt lgkmcnt(0)
	v_sub_f32_e32 v76, v208, v76
	v_sub_f32_e32 v77, v208, v77
	v_sub_f32_e32 v78, v208, v78
	v_sub_f32_e32 v79, v208, v79
	s_mov_b64 s[60:61], -1
	s_and_b64 vcc, exec, s[52:53]
	s_cbranch_vccz .LBB0_294
	s_cmp_ge_i32 s40, s12
	s_cbranch_scc0 .LBB0_248
	s_waitcnt vmcnt(0) lgkmcnt(0)
	s_barrier
	s_mov_b64 s[60:61], 0

.LBB0_260:
	s_waitcnt lgkmcnt(14)
	v_mfma_f32_32x32x16_bf16 v[16:31], v[126:129], v[190:193], v[16:31]
	v_cndmask_b32_e64 v190, 0, 1, s[62:63]
	v_exp_f32_e32 v80, v80
	v_exp_f32_e32 v81, v81
	v_exp_f32_e32 v82, v82
	v_exp_f32_e32 v83, v83
	v_cmp_ne_u32_e64 s[40:41], 1, v190
	s_andn2_b64 vcc, exec, s[62:63]
	s_cbranch_vccnz .LBB0_262
	ds_read_b128 v[32:35], v242 offset:256
	s_waitcnt lgkmcnt(0)
	v_sub_f32_e32 v32, v208, v32
	v_sub_f32_e32 v33, v208, v33
	v_sub_f32_e32 v34, v208, v34
	v_sub_f32_e32 v35, v208, v35
.LBB0_262:
	s_waitcnt lgkmcnt(12)
	v_mfma_f32_32x32x16_bf16 v[0:15], v[126:129], v[186:189], v[0:15]
	v_exp_f32_e32 v84, v84
	v_exp_f32_e32 v85, v85
	v_exp_f32_e32 v86, v86
	v_exp_f32_e32 v87, v87
	s_and_b64 vcc, exec, s[40:41]
	s_cbranch_vccnz .LBB0_264
	ds_read_b128 v[36:39], v242 offset:288
	s_waitcnt lgkmcnt(0)
	v_sub_f32_e32 v36, v208, v36
	v_sub_f32_e32 v37, v208, v37
	v_sub_f32_e32 v38, v208, v38
	v_sub_f32_e32 v39, v208, v39

.LBB0_266:
	s_waitcnt lgkmcnt(10)
	v_mfma_f32_32x32x16_bf16 v[16:31], v[122:125], v[182:185], v[16:31]
	v_exp_f32_e32 v88, v88
	v_exp_f32_e32 v89, v89
	v_exp_f32_e32 v90, v90
	v_exp_f32_e32 v91, v91
	s_and_b64 vcc, exec, s[40:41]
	s_cbranch_vccnz .LBB0_268
	ds_read_b128 v[40:43], v242 offset:320
	s_waitcnt lgkmcnt(0)
	v_sub_f32_e32 v40, v208, v40
	v_sub_f32_e32 v41, v208, v41
	v_sub_f32_e32 v42, v208, v42
	v_sub_f32_e32 v43, v208, v43

.LBB0_270:
	s_waitcnt lgkmcnt(8)
	v_mfma_f32_32x32x16_bf16 v[0:15], v[122:125], v[178:181], v[0:15]
	v_exp_f32_e32 v92, v92
	v_exp_f32_e32 v93, v93
	v_exp_f32_e32 v94, v94
	v_exp_f32_e32 v95, v95
	s_and_b64 vcc, exec, s[40:41]
	s_cbranch_vccnz .LBB0_272
	ds_read_b128 v[44:47], v242 offset:352
	s_waitcnt lgkmcnt(0)
	v_sub_f32_e32 v44, v208, v44
	v_sub_f32_e32 v45, v208, v45
	v_sub_f32_e32 v46, v208, v46
	v_sub_f32_e32 v47, v208, v47

.LBB0_274:
	s_waitcnt lgkmcnt(6)
	v_mfma_f32_32x32x16_bf16 v[16:31], v[118:121], v[174:177], v[16:31]
	v_exp_f32_e32 v64, v64
	v_exp_f32_e32 v65, v65
	v_exp_f32_e32 v66, v66
	v_exp_f32_e32 v67, v67
	s_and_b64 vcc, exec, s[40:41]
	s_cbranch_vccnz .LBB0_276
	ds_read_b128 v[48:51], v242 offset:384
	s_waitcnt lgkmcnt(0)
	v_sub_f32_e32 v48, v208, v48
	v_sub_f32_e32 v49, v208, v49
	v_sub_f32_e32 v50, v208, v50
	v_sub_f32_e32 v51, v208, v51

.LBB0_278:
	s_waitcnt lgkmcnt(4)
	v_mfma_f32_32x32x16_bf16 v[0:15], v[118:121], v[170:173], v[0:15]
	v_exp_f32_e32 v68, v68
	v_exp_f32_e32 v69, v69
	v_exp_f32_e32 v70, v70
	v_exp_f32_e32 v71, v71
	s_and_b64 vcc, exec, s[40:41]
	s_cbranch_vccnz .LBB0_280
	ds_read_b128 v[52:55], v242 offset:416
	s_waitcnt lgkmcnt(0)
	v_sub_f32_e32 v52, v208, v52
	v_sub_f32_e32 v53, v208, v53
	v_sub_f32_e32 v54, v208, v54
	v_sub_f32_e32 v55, v208, v55
.LBB0_280:
	s_waitcnt lgkmcnt(2)
	v_mfma_f32_32x32x16_bf16 v[16:31], v[114:117], v[166:169], v[16:31]
	v_exp_f32_e32 v72, v72
	v_exp_f32_e32 v73, v73
	v_exp_f32_e32 v74, v74
	v_exp_f32_e32 v75, v75
	s_and_b64 vcc, exec, s[40:41]
	s_cbranch_vccnz .LBB0_282
	ds_read_b128 v[56:59], v242 offset:448
	s_waitcnt lgkmcnt(0)
	v_sub_f32_e32 v56, v208, v56
	v_sub_f32_e32 v57, v208, v57
	v_sub_f32_e32 v58, v208, v58
	v_sub_f32_e32 v59, v208, v59
.LBB0_282:
	s_waitcnt lgkmcnt(0)
	v_mfma_f32_32x32x16_bf16 v[0:15], v[114:117], v[162:165], v[0:15]
	v_exp_f32_e32 v76, v76
	v_exp_f32_e32 v77, v77
	v_exp_f32_e32 v78, v78
	v_exp_f32_e32 v79, v79
	s_and_b64 vcc, exec, s[40:41]
	s_cbranch_vccnz .LBB0_284
	ds_read_b128 v[60:63], v242 offset:480
	s_waitcnt lgkmcnt(0)
	v_sub_f32_e32 v60, v208, v60
	v_sub_f32_e32 v61, v208, v61
	v_sub_f32_e32 v62, v208, v62
	v_sub_f32_e32 v63, v208, v63
